# W2GU seam conversion concentrated on seams 0 and 1 (two items per wave back to back, four waves) instead of one item per wave on seams 0-3
# baseline (speedup 1.0000x reference)
; #define LAS __attribute__((address_space(3)))
; #define TR_LOAD(p) __builtin_nontemporal_load(p)
; __device__ __forceinline__ TrItem tr_decode(int it, const float* const* in, unsigned char* ws, int lane) {
;     ...
;     const int rh = r >> 3, rl = r & 7, nq = ndb >> DL, kbh = rh / nq, dbh = rh - kbh * nq;
;     const int kb = (kbh << KL) + (rl >> DL), db = (dbh << DL) + (rl & ((1 << DL) - 1)), d0 = db * 64, k0 = kb * 64;
;     ...
;     const int kb = r / ndb, db = r - kb * ndb, d0 = db * 64, k0 = kb * 64;
;     ...
;     const int blk = d0 + 32 * ((lane & 15) >> 3);
;     const float* src = W; int s0 = blk;
;     if (kind == 1) { const int pn = blk >> 8, bj = (blk >> 7) & 1, o = blk & 127; src = bj ? W2 : W; s0 = pn * 128 + o; }
;     else if (kind == 2) s0 = win_src(blk);
;     TrItem t; t.src = src + (size_t)(k0 + (lane >> 4)) * N + s0 + 4 * (lane & 7); t.gain = gain ? gain + k0 + 8 * (lane & 7) : nullptr;
;     t.dst = WT + (size_t)(d0 + (lane >> 3)) * K + k0 + 8 * (lane & 7); t.N = N; t.K = K; t.nts = nts && TR_NTS;
; __device__ __forceinline__ void tr_all(const float* const* in, unsigned char* ws, LAS float* scr, int gw, int ngw, int lane, const TrRanges rg) {
;     ...
;     for (int i = 0; i < 16; ++i) v[i] = TR_LOAD((const f32x4*)(cur.src + (size_t)(4 * i) * cur.N));
;     for (int it = gw; it < TR_CNT; it += ngw) {
;         const int nit = it + ngw; const bool hn = nit < TR_CNT;
;         TrItem nx = cur; f32x4 w[16];
;         if (hn) { nx = tr_decode(rg.item(nit), in, ws, lane);
; #pragma unroll
;             for (int i = 0; i < 16; ++i) w[i] = TR_LOAD((const f32x4*)(nx.src + (size_t)(4 * i) * nx.N)); }
;         LAS float* wp = scr + (lane >> 4) * 65 + 4 * (lane & 15);
; #pragma unroll
;         for (int i = 0; i < 16; ++i) { wp[(4 * i) * 65 + 0] = v[i][0]; wp[(4 * i) * 65 + 1] = v[i][1]; wp[(4 * i) * 65 + 2] = v[i][2]; wp[(4 * i) * 65 + 3] = v[i][3]; }
;         f32x4 g0 = {1.f, 1.f, 1.f, 1.f}, g1 = {1.f, 1.f, 1.f, 1.f};
;         if (cur.gain) { g0 = *(const f32x4*)cur.gain; g1 = *(const f32x4*)(cur.gain + 4); }
.Lseam_cv_0:
	s_cmp_lt_u32 s98, 2
	s_cbranch_scc1 .LBB0_339
	s_cmp_gt_u32 s98, 5
	s_cbranch_scc1 .Lseam_cv_0_1
	s_mov_b64 exec, -1
	s_lshl_b32 s99, s87, 2
	s_add_i32 s99, s99, s98
	s_add_i32 s99, s99, 0x5fe
	s_lshr_b32 s100, s99, 3
	s_mul_i32 s101, s100, 0x5d2
	s_lshr_b32 s101, s101, 16
	s_mul_i32 vcc_lo, s101, 44
	s_sub_i32 s100, s100, vcc_lo
	s_and_b32 vcc_lo, s99, 7
	s_lshr_b32 vcc_hi, vcc_lo, 2
	s_lshl_b32 s101, s101, 1
	s_add_i32 s101, s101, vcc_hi
	s_and_b32 vcc_lo, vcc_lo, 3
	s_lshl_b32 s100, s100, 2
	s_add_i32 s100, s100, vcc_lo
	s_lshl_b32 s101, s101, 6
	s_lshl_b32 s100, s100, 6
	v_and_b32_e32 v66, 63, v1
	v_lshrrev_b32_e32 v67, 4, v66
	v_and_b32_e32 v68, 15, v66
	v_and_b32_e32 v73, 7, v66
	v_lshrrev_b32_e32 v72, 3, v66
	s_mul_i32 s99, s98, 0x4100
	v_mul_u32_u24_e32 v70, 0x104, v67
	v_lshl_add_u32 v70, v68, 4, v70
	v_add_u32_e32 v70, s99, v70
	v_mul_u32_u24_e32 v71, 0x820, v73
	v_lshl_add_u32 v71, v72, 2, v71
	v_add_u32_e32 v71, s99, v71
	s_mul_i32 s99, s101, 0x1600
	s_lshr_b32 vcc_lo, s100, 8
	s_lshl_b32 vcc_lo, vcc_lo, 7
	s_add_i32 s99, s99, vcc_lo
	s_and_b32 vcc_lo, s100, 0x7f
	s_add_i32 s99, s99, vcc_lo
	s_lshl_b32 s99, s99, 2
	v_mul_u32_u24_e32 v69, 0x5800, v67
	v_lshl_add_u32 v69, v68, 4, v69
	v_add_u32_e32 v69, s99, v69
	s_lshl_b32 s99, s100, 12
	s_lshl_b32 vcc_lo, s101, 1
	s_add_i32 s99, s99, vcc_lo
	v_lshlrev_b32_e32 v72, 12, v72
	v_lshl_add_u32 v72, v73, 4, v72
	v_add_u32_e32 v72, s99, v72
	s_lshl_b32 s99, s101, 2
	v_lshlrev_b32_e32 v73, 5, v73
	v_add_u32_e32 v73, s99, v73
	s_nop 0
	s_bitcmp1_b32 s100, 7
	v_readlane_b32 s100, v254, 6
	v_readlane_b32 s101, v254, 7
	v_readlane_b32 s98, v254, 8
	v_readlane_b32 s99, v254, 9
	s_nop 3
	s_cselect_b32 s100, s98, s100
	s_cselect_b32 s101, s99, s101
	v_readlane_b32 s98, v254, 4
	v_readlane_b32 s99, v254, 5
	global_load_dwordx4 v[2:5], v69, s[100:101] nt
	v_add_u32_e32 v68, 0x16000, v69
	global_load_dwordx4 v[6:9], v68, s[100:101] nt
	v_add_u32_e32 v67, 0x2c000, v69
	global_load_dwordx4 v[10:13], v67, s[100:101] nt
	v_add_u32_e32 v68, 0x42000, v69
	global_load_dwordx4 v[14:17], v68, s[100:101] nt
	v_add_u32_e32 v67, 0x58000, v69
	global_load_dwordx4 v[18:21], v67, s[100:101] nt
	v_add_u32_e32 v68, 0x6e000, v69
	global_load_dwordx4 v[22:25], v68, s[100:101] nt
	v_add_u32_e32 v67, 0x84000, v69
	global_load_dwordx4 v[26:29], v67, s[100:101] nt
	v_add_u32_e32 v68, 0x9a000, v69
	global_load_dwordx4 v[30:33], v68, s[100:101] nt
	v_add_u32_e32 v67, 0xb0000, v69
	global_load_dwordx4 v[34:37], v67, s[100:101] nt
	v_add_u32_e32 v68, 0xc6000, v69
	global_load_dwordx4 v[38:41], v68, s[100:101] nt
	v_add_u32_e32 v67, 0xdc000, v69
	global_load_dwordx4 v[42:45], v67, s[100:101] nt
	v_add_u32_e32 v68, 0xf2000, v69
	global_load_dwordx4 v[46:49], v68, s[100:101] nt
	v_add_u32_e32 v67, 0x108000, v69
	global_load_dwordx4 v[50:53], v67, s[100:101] nt
	v_add_u32_e32 v68, 0x11e000, v69
	global_load_dwordx4 v[54:57], v68, s[100:101] nt
	v_add_u32_e32 v67, 0x134000, v69
	global_load_dwordx4 v[58:61], v67, s[100:101] nt
	v_add_u32_e32 v68, 0x14a000, v69
	global_load_dwordx4 v[62:65], v68, s[100:101] nt
	global_load_dwordx4 v[74:77], v73, s[98:99]
	global_load_dwordx4 v[78:81], v73, s[98:99] offset:16
	s_waitcnt vmcnt(17)
	ds_write_b32 v70, v2
	ds_write_b32 v70, v3 offset:4
	ds_write_b32 v70, v4 offset:8
	ds_write_b32 v70, v5 offset:12
	s_waitcnt vmcnt(16)
	ds_write_b32 v70, v6 offset:1040
	ds_write_b32 v70, v7 offset:1044
	ds_write_b32 v70, v8 offset:1048
	ds_write_b32 v70, v9 offset:1052
	s_waitcnt vmcnt(15)
	ds_write_b32 v70, v10 offset:2080
	ds_write_b32 v70, v11 offset:2084
	ds_write_b32 v70, v12 offset:2088
	ds_write_b32 v70, v13 offset:2092
	s_waitcnt vmcnt(14)
	ds_write_b32 v70, v14 offset:3120
	ds_write_b32 v70, v15 offset:3124
	ds_write_b32 v70, v16 offset:3128
	ds_write_b32 v70, v17 offset:3132
	s_waitcnt vmcnt(13)
	ds_write_b32 v70, v18 offset:4160
	ds_write_b32 v70, v19 offset:4164
	ds_write_b32 v70, v20 offset:4168
	ds_write_b32 v70, v21 offset:4172
	s_waitcnt vmcnt(12)
	ds_write_b32 v70, v22 offset:5200
	ds_write_b32 v70, v23 offset:5204
	ds_write_b32 v70, v24 offset:5208
	ds_write_b32 v70, v25 offset:5212
	s_waitcnt vmcnt(11)
	ds_write_b32 v70, v26 offset:6240
	ds_write_b32 v70, v27 offset:6244
	ds_write_b32 v70, v28 offset:6248
	ds_write_b32 v70, v29 offset:6252
	s_waitcnt vmcnt(10)
	ds_write_b32 v70, v30 offset:7280
	ds_write_b32 v70, v31 offset:7284
	ds_write_b32 v70, v32 offset:7288
	ds_write_b32 v70, v33 offset:7292
	s_waitcnt vmcnt(9)
	ds_write_b32 v70, v34 offset:8320
	ds_write_b32 v70, v35 offset:8324
	ds_write_b32 v70, v36 offset:8328
	ds_write_b32 v70, v37 offset:8332
	s_waitcnt vmcnt(8)
	ds_write_b32 v70, v38 offset:9360
	ds_write_b32 v70, v39 offset:9364
	ds_write_b32 v70, v40 offset:9368
	ds_write_b32 v70, v41 offset:9372
	s_waitcnt vmcnt(7)
	ds_write_b32 v70, v42 offset:10400
	ds_write_b32 v70, v43 offset:10404
	ds_write_b32 v70, v44 offset:10408
	ds_write_b32 v70, v45 offset:10412
	s_waitcnt vmcnt(6)
	ds_write_b32 v70, v46 offset:11440
	ds_write_b32 v70, v47 offset:11444
	ds_write_b32 v70, v48 offset:11448
	ds_write_b32 v70, v49 offset:11452
	s_waitcnt vmcnt(5)
	ds_write_b32 v70, v50 offset:12480
	ds_write_b32 v70, v51 offset:12484
	ds_write_b32 v70, v52 offset:12488
	ds_write_b32 v70, v53 offset:12492
	s_waitcnt vmcnt(4)
	ds_write_b32 v70, v54 offset:13520
	ds_write_b32 v70, v55 offset:13524
	ds_write_b32 v70, v56 offset:13528
	ds_write_b32 v70, v57 offset:13532
	s_waitcnt vmcnt(3)
	ds_write_b32 v70, v58 offset:14560
	ds_write_b32 v70, v59 offset:14564
	ds_write_b32 v70, v60 offset:14568
	ds_write_b32 v70, v61 offset:14572
	s_waitcnt vmcnt(2)
; #define LAS __attribute__((address_space(3)))
; __device__ __forceinline__ unsigned cvtpk(float lo, float hi) { f32x2_t v = {lo, hi}; bf16x2_t b = __builtin_convertvector(v, bf16x2_t); return __builtin_bit_cast(unsigned, b); }
; __device__ __forceinline__ void tr_all(const float* const* in, unsigned char* ws, LAS float* scr, int gw, int ngw, int lane, const TrRanges rg) {
;     ...
;         const LAS float* rp = scr + (8 * (lane & 7)) * 65 + (lane >> 3);
; #pragma unroll
;         for (int j = 0; j < 8; ++j) { const LAS float* s = rp + 8 * j;
;             u32x4 o; o.x = cvtpk(s[0 * 65] * g0[0], s[1 * 65] * g0[1]); o.y = cvtpk(s[2 * 65] * g0[2], s[3 * 65] * g0[3]);
;             o.z = cvtpk(s[4 * 65] * g1[0], s[5 * 65] * g1[1]); o.w = cvtpk(s[6 * 65] * g1[2], s[7 * 65] * g1[3]);
;             if (cur.nts) __builtin_nontemporal_store(o, (u32x4*)(cur.dst + (size_t)(8 * j) * cur.K)); else *(u32x4*)(cur.dst + (size_t)(8 * j) * cur.K) = o; }
	ds_write_b32 v70, v62 offset:15600
	ds_write_b32 v70, v63 offset:15604
	ds_write_b32 v70, v64 offset:15608
	ds_write_b32 v70, v65 offset:15612
	s_add_u32 s100, s84, 0x8f00000
	s_addc_u32 s101, s85, 0
	s_waitcnt vmcnt(0) lgkmcnt(0)
	ds_read_b32 v2, v71
	ds_read_b32 v3, v71 offset:260
	ds_read_b32 v4, v71 offset:520
	ds_read_b32 v5, v71 offset:780
	ds_read_b32 v6, v71 offset:1040
	ds_read_b32 v7, v71 offset:1300
	ds_read_b32 v8, v71 offset:1560
	ds_read_b32 v9, v71 offset:1820
	ds_read_b32 v10, v71 offset:32
	ds_read_b32 v11, v71 offset:292
	ds_read_b32 v12, v71 offset:552
	ds_read_b32 v13, v71 offset:812
	ds_read_b32 v14, v71 offset:1072
	ds_read_b32 v15, v71 offset:1332
	ds_read_b32 v16, v71 offset:1592
	ds_read_b32 v17, v71 offset:1852
	ds_read_b32 v18, v71 offset:64
	ds_read_b32 v19, v71 offset:324
	ds_read_b32 v20, v71 offset:584
	ds_read_b32 v21, v71 offset:844
	ds_read_b32 v22, v71 offset:1104
	ds_read_b32 v23, v71 offset:1364
	ds_read_b32 v24, v71 offset:1624
	ds_read_b32 v25, v71 offset:1884
	ds_read_b32 v26, v71 offset:96
	ds_read_b32 v27, v71 offset:356
	ds_read_b32 v28, v71 offset:616
	ds_read_b32 v29, v71 offset:876
	ds_read_b32 v30, v71 offset:1136
	ds_read_b32 v31, v71 offset:1396
	ds_read_b32 v32, v71 offset:1656
	ds_read_b32 v33, v71 offset:1916
	ds_read_b32 v34, v71 offset:128
	ds_read_b32 v35, v71 offset:388
	ds_read_b32 v36, v71 offset:648
	ds_read_b32 v37, v71 offset:908
	ds_read_b32 v38, v71 offset:1168
	ds_read_b32 v39, v71 offset:1428
	ds_read_b32 v40, v71 offset:1688
	ds_read_b32 v41, v71 offset:1948
	ds_read_b32 v42, v71 offset:160
	ds_read_b32 v43, v71 offset:420
	ds_read_b32 v44, v71 offset:680
	ds_read_b32 v45, v71 offset:940
	ds_read_b32 v46, v71 offset:1200
	ds_read_b32 v47, v71 offset:1460
	ds_read_b32 v48, v71 offset:1720
	ds_read_b32 v49, v71 offset:1980
	ds_read_b32 v50, v71 offset:192
	ds_read_b32 v51, v71 offset:452
	ds_read_b32 v52, v71 offset:712
	ds_read_b32 v53, v71 offset:972
	ds_read_b32 v54, v71 offset:1232
	ds_read_b32 v55, v71 offset:1492
	ds_read_b32 v56, v71 offset:1752
	ds_read_b32 v57, v71 offset:2012
	ds_read_b32 v58, v71 offset:224
	ds_read_b32 v59, v71 offset:484
	ds_read_b32 v60, v71 offset:744
	ds_read_b32 v61, v71 offset:1004
	ds_read_b32 v62, v71 offset:1264
	ds_read_b32 v63, v71 offset:1524
	ds_read_b32 v64, v71 offset:1784
	ds_read_b32 v65, v71 offset:2044
	s_waitcnt lgkmcnt(15)
	v_mul_f32_e32 v2, v2, v74
	v_mul_f32_e32 v3, v3, v75
	v_mul_f32_e32 v4, v4, v76
	v_mul_f32_e32 v5, v5, v77
	v_mul_f32_e32 v6, v6, v78
	v_mul_f32_e32 v7, v7, v79
	v_mul_f32_e32 v8, v8, v80
	v_mul_f32_e32 v9, v9, v81
	v_cvt_pk_bf16_f32 v192, v2, v3
	v_cvt_pk_bf16_f32 v193, v4, v5
	v_cvt_pk_bf16_f32 v194, v6, v7
	v_cvt_pk_bf16_f32 v195, v8, v9
	global_store_dwordx4 v72, v[192:195], s[100:101] nt
	s_waitcnt lgkmcnt(15)
	v_mul_f32_e32 v10, v10, v74
	v_mul_f32_e32 v11, v11, v75
	v_mul_f32_e32 v12, v12, v76
	v_mul_f32_e32 v13, v13, v77
	v_mul_f32_e32 v14, v14, v78
	v_mul_f32_e32 v15, v15, v79
	v_mul_f32_e32 v16, v16, v80
	v_mul_f32_e32 v17, v17, v81
	v_cvt_pk_bf16_f32 v196, v10, v11
	v_cvt_pk_bf16_f32 v197, v12, v13
	v_cvt_pk_bf16_f32 v198, v14, v15
	v_cvt_pk_bf16_f32 v199, v16, v17
	v_add_u32_e32 v68, 0x8000, v72
	global_store_dwordx4 v68, v[196:199], s[100:101] nt
	s_waitcnt lgkmcnt(15)
	v_mul_f32_e32 v18, v18, v74
	v_mul_f32_e32 v19, v19, v75
	v_mul_f32_e32 v20, v20, v76
	v_mul_f32_e32 v21, v21, v77
	v_mul_f32_e32 v22, v22, v78
	v_mul_f32_e32 v23, v23, v79
	v_mul_f32_e32 v24, v24, v80
	v_mul_f32_e32 v25, v25, v81
	v_cvt_pk_bf16_f32 v200, v18, v19
	v_cvt_pk_bf16_f32 v201, v20, v21
	v_cvt_pk_bf16_f32 v202, v22, v23
	v_cvt_pk_bf16_f32 v203, v24, v25
	v_add_u32_e32 v67, 0x10000, v72
	global_store_dwordx4 v67, v[200:203], s[100:101] nt
	s_waitcnt lgkmcnt(15)
	v_mul_f32_e32 v26, v26, v74
	v_mul_f32_e32 v27, v27, v75
	v_mul_f32_e32 v28, v28, v76
	v_mul_f32_e32 v29, v29, v77
	v_mul_f32_e32 v30, v30, v78
	v_mul_f32_e32 v31, v31, v79
	v_mul_f32_e32 v32, v32, v80
	v_mul_f32_e32 v33, v33, v81
	v_cvt_pk_bf16_f32 v204, v26, v27
	v_cvt_pk_bf16_f32 v205, v28, v29
	v_cvt_pk_bf16_f32 v206, v30, v31
	v_cvt_pk_bf16_f32 v207, v32, v33
	v_add_u32_e32 v68, 0x18000, v72
	global_store_dwordx4 v68, v[204:207], s[100:101] nt
	s_waitcnt lgkmcnt(15)
	v_mul_f32_e32 v34, v34, v74
	v_mul_f32_e32 v35, v35, v75
	v_mul_f32_e32 v36, v36, v76
	v_mul_f32_e32 v37, v37, v77
	v_mul_f32_e32 v38, v38, v78
	v_mul_f32_e32 v39, v39, v79
	v_mul_f32_e32 v40, v40, v80
	v_mul_f32_e32 v41, v41, v81
	v_cvt_pk_bf16_f32 v208, v34, v35
	v_cvt_pk_bf16_f32 v209, v36, v37
	v_cvt_pk_bf16_f32 v210, v38, v39
	v_cvt_pk_bf16_f32 v211, v40, v41
	v_add_u32_e32 v67, 0x20000, v72
	global_store_dwordx4 v67, v[208:211], s[100:101] nt
	s_waitcnt lgkmcnt(15)
	v_mul_f32_e32 v42, v42, v74
	v_mul_f32_e32 v43, v43, v75
	v_mul_f32_e32 v44, v44, v76
	v_mul_f32_e32 v45, v45, v77
	v_mul_f32_e32 v46, v46, v78
	v_mul_f32_e32 v47, v47, v79
	v_mul_f32_e32 v48, v48, v80
	v_mul_f32_e32 v49, v49, v81
	v_cvt_pk_bf16_f32 v212, v42, v43
	v_cvt_pk_bf16_f32 v213, v44, v45
	v_cvt_pk_bf16_f32 v214, v46, v47
	v_cvt_pk_bf16_f32 v215, v48, v49
	v_add_u32_e32 v68, 0x28000, v72
	global_store_dwordx4 v68, v[212:215], s[100:101] nt
	s_waitcnt lgkmcnt(8)
	v_mul_f32_e32 v50, v50, v74
	v_mul_f32_e32 v51, v51, v75
	v_mul_f32_e32 v52, v52, v76
	v_mul_f32_e32 v53, v53, v77
	v_mul_f32_e32 v54, v54, v78
	v_mul_f32_e32 v55, v55, v79
	v_mul_f32_e32 v56, v56, v80
	v_mul_f32_e32 v57, v57, v81
	v_cvt_pk_bf16_f32 v216, v50, v51
	v_cvt_pk_bf16_f32 v217, v52, v53
	v_cvt_pk_bf16_f32 v218, v54, v55
	v_cvt_pk_bf16_f32 v219, v56, v57
	v_add_u32_e32 v67, 0x30000, v72
	global_store_dwordx4 v67, v[216:219], s[100:101] nt
	s_waitcnt lgkmcnt(0)
; #define LAS __attribute__((address_space(3)))
; #define TR_LOAD(p) __builtin_nontemporal_load(p)
; __device__ __forceinline__ TrItem tr_decode(int it, const float* const* in, unsigned char* ws, int lane) {
;     ...
;     const int rh = r >> 3, rl = r & 7, nq = ndb >> DL, kbh = rh / nq, dbh = rh - kbh * nq;
;     const int kb = (kbh << KL) + (rl >> DL), db = (dbh << DL) + (rl & ((1 << DL) - 1)), d0 = db * 64, k0 = kb * 64;
;     ...
;     const int kb = r / ndb, db = r - kb * ndb, d0 = db * 64, k0 = kb * 64;
;     ...
;     const int blk = d0 + 32 * ((lane & 15) >> 3);
;     const float* src = W; int s0 = blk;
;     if (kind == 1) { const int pn = blk >> 8, bj = (blk >> 7) & 1, o = blk & 127; src = bj ? W2 : W; s0 = pn * 128 + o; }
;     else if (kind == 2) s0 = win_src(blk);
;     TrItem t; t.src = src + (size_t)(k0 + (lane >> 4)) * N + s0 + 4 * (lane & 7); t.gain = gain ? gain + k0 + 8 * (lane & 7) : nullptr;
;     t.dst = WT + (size_t)(d0 + (lane >> 3)) * K + k0 + 8 * (lane & 7); t.N = N; t.K = K; t.nts = nts && TR_NTS;
; __device__ __forceinline__ void tr_all(const float* const* in, unsigned char* ws, LAS float* scr, int gw, int ngw, int lane, const TrRanges rg) {
;     ...
;     for (int i = 0; i < 16; ++i) v[i] = TR_LOAD((const f32x4*)(cur.src + (size_t)(4 * i) * cur.N));
;     for (int it = gw; it < TR_CNT; it += ngw) {
;         const int nit = it + ngw; const bool hn = nit < TR_CNT;
;         TrItem nx = cur; f32x4 w[16];
;         if (hn) { nx = tr_decode(rg.item(nit), in, ws, lane);
; #pragma unroll
;             for (int i = 0; i < 16; ++i) w[i] = TR_LOAD((const f32x4*)(nx.src + (size_t)(4 * i) * nx.N)); }
;         LAS float* wp = scr + (lane >> 4) * 65 + 4 * (lane & 15);
; #pragma unroll
;         for (int i = 0; i < 16; ++i) { wp[(4 * i) * 65 + 0] = v[i][0]; wp[(4 * i) * 65 + 1] = v[i][1]; wp[(4 * i) * 65 + 2] = v[i][2]; wp[(4 * i) * 65 + 3] = v[i][3]; }
	v_mul_f32_e32 v58, v58, v74
	v_mul_f32_e32 v59, v59, v75
	v_mul_f32_e32 v60, v60, v76
	v_mul_f32_e32 v61, v61, v77
	v_mul_f32_e32 v62, v62, v78
	v_mul_f32_e32 v63, v63, v79
	v_mul_f32_e32 v64, v64, v80
	v_mul_f32_e32 v65, v65, v81
	v_cvt_pk_bf16_f32 v220, v58, v59
	v_cvt_pk_bf16_f32 v221, v60, v61
	v_cvt_pk_bf16_f32 v222, v62, v63
	v_cvt_pk_bf16_f32 v223, v64, v65
	v_add_u32_e32 v68, 0x38000, v72
	global_store_dwordx4 v68, v[220:223], s[100:101] nt
	v_readfirstlane_b32 s98, v1
	s_nop 3
	s_lshr_b32 s98, s98, 6
	s_lshl_b32 s99, s87, 2
	s_add_i32 s99, s99, s98
	s_add_i32 s99, s99, 0x9fe
	s_lshr_b32 s100, s99, 3
	s_mul_i32 s101, s100, 0x5d2
	s_lshr_b32 s101, s101, 16
	s_mul_i32 vcc_lo, s101, 44
	s_sub_i32 s100, s100, vcc_lo
	s_and_b32 vcc_lo, s99, 7
	s_lshr_b32 vcc_hi, vcc_lo, 2
	s_lshl_b32 s101, s101, 1
	s_add_i32 s101, s101, vcc_hi
	s_and_b32 vcc_lo, vcc_lo, 3
	s_lshl_b32 s100, s100, 2
	s_add_i32 s100, s100, vcc_lo
	s_lshl_b32 s101, s101, 6
	s_lshl_b32 s100, s100, 6
	v_and_b32_e32 v66, 63, v1
	v_lshrrev_b32_e32 v67, 4, v66
	v_and_b32_e32 v68, 15, v66
	v_and_b32_e32 v73, 7, v66
	v_lshrrev_b32_e32 v72, 3, v66
	s_mul_i32 s99, s98, 0x4100
	v_mul_u32_u24_e32 v70, 0x104, v67
	v_lshl_add_u32 v70, v68, 4, v70
	v_add_u32_e32 v70, s99, v70
	v_mul_u32_u24_e32 v71, 0x820, v73
	v_lshl_add_u32 v71, v72, 2, v71
	v_add_u32_e32 v71, s99, v71
	s_mul_i32 s99, s101, 0x1600
	s_lshr_b32 vcc_lo, s100, 8
	s_lshl_b32 vcc_lo, vcc_lo, 7
	s_add_i32 s99, s99, vcc_lo
	s_and_b32 vcc_lo, s100, 0x7f
	s_add_i32 s99, s99, vcc_lo
	s_lshl_b32 s99, s99, 2
	v_mul_u32_u24_e32 v69, 0x5800, v67
	v_lshl_add_u32 v69, v68, 4, v69
	v_add_u32_e32 v69, s99, v69
	s_lshl_b32 s99, s100, 12
	s_lshl_b32 vcc_lo, s101, 1
	s_add_i32 s99, s99, vcc_lo
	v_lshlrev_b32_e32 v72, 12, v72
	v_lshl_add_u32 v72, v73, 4, v72
	v_add_u32_e32 v72, s99, v72
	s_lshl_b32 s99, s101, 2
	v_lshlrev_b32_e32 v73, 5, v73
	v_add_u32_e32 v73, s99, v73
	s_nop 0
	s_bitcmp1_b32 s100, 7
	v_readlane_b32 s100, v254, 6
	v_readlane_b32 s101, v254, 7
	v_readlane_b32 s98, v254, 8
	v_readlane_b32 s99, v254, 9
	s_nop 3
	s_cselect_b32 s100, s98, s100
	s_cselect_b32 s101, s99, s101
	v_readlane_b32 s98, v254, 4
	v_readlane_b32 s99, v254, 5
	global_load_dwordx4 v[2:5], v69, s[100:101] nt
	v_add_u32_e32 v68, 0x16000, v69
	global_load_dwordx4 v[6:9], v68, s[100:101] nt
	v_add_u32_e32 v67, 0x2c000, v69
	global_load_dwordx4 v[10:13], v67, s[100:101] nt
	v_add_u32_e32 v68, 0x42000, v69
	global_load_dwordx4 v[14:17], v68, s[100:101] nt
	v_add_u32_e32 v67, 0x58000, v69
	global_load_dwordx4 v[18:21], v67, s[100:101] nt
	v_add_u32_e32 v68, 0x6e000, v69
	global_load_dwordx4 v[22:25], v68, s[100:101] nt
	v_add_u32_e32 v67, 0x84000, v69
	global_load_dwordx4 v[26:29], v67, s[100:101] nt
	v_add_u32_e32 v68, 0x9a000, v69
	global_load_dwordx4 v[30:33], v68, s[100:101] nt
	v_add_u32_e32 v67, 0xb0000, v69
	global_load_dwordx4 v[34:37], v67, s[100:101] nt
	v_add_u32_e32 v68, 0xc6000, v69
	global_load_dwordx4 v[38:41], v68, s[100:101] nt
	v_add_u32_e32 v67, 0xdc000, v69
	global_load_dwordx4 v[42:45], v67, s[100:101] nt
	v_add_u32_e32 v68, 0xf2000, v69
	global_load_dwordx4 v[46:49], v68, s[100:101] nt
	v_add_u32_e32 v67, 0x108000, v69
	global_load_dwordx4 v[50:53], v67, s[100:101] nt
	v_add_u32_e32 v68, 0x11e000, v69
	global_load_dwordx4 v[54:57], v68, s[100:101] nt
	v_add_u32_e32 v67, 0x134000, v69
	global_load_dwordx4 v[58:61], v67, s[100:101] nt
	v_add_u32_e32 v68, 0x14a000, v69
	global_load_dwordx4 v[62:65], v68, s[100:101] nt
	global_load_dwordx4 v[74:77], v73, s[98:99]
	global_load_dwordx4 v[78:81], v73, s[98:99] offset:16
	s_waitcnt vmcnt(17)
	ds_write_b32 v70, v2
	ds_write_b32 v70, v3 offset:4
	ds_write_b32 v70, v4 offset:8
	ds_write_b32 v70, v5 offset:12
	s_waitcnt vmcnt(16)
	ds_write_b32 v70, v6 offset:1040
	ds_write_b32 v70, v7 offset:1044
	ds_write_b32 v70, v8 offset:1048
	ds_write_b32 v70, v9 offset:1052
	s_waitcnt vmcnt(15)
	ds_write_b32 v70, v10 offset:2080
	ds_write_b32 v70, v11 offset:2084
	ds_write_b32 v70, v12 offset:2088
	ds_write_b32 v70, v13 offset:2092
	s_waitcnt vmcnt(14)
	ds_write_b32 v70, v14 offset:3120
	ds_write_b32 v70, v15 offset:3124
	ds_write_b32 v70, v16 offset:3128
	ds_write_b32 v70, v17 offset:3132
	s_waitcnt vmcnt(13)
	ds_write_b32 v70, v18 offset:4160
	ds_write_b32 v70, v19 offset:4164
	ds_write_b32 v70, v20 offset:4168
	ds_write_b32 v70, v21 offset:4172
	s_waitcnt vmcnt(12)
	ds_write_b32 v70, v22 offset:5200
	ds_write_b32 v70, v23 offset:5204
	ds_write_b32 v70, v24 offset:5208
	ds_write_b32 v70, v25 offset:5212
	s_waitcnt vmcnt(11)
	ds_write_b32 v70, v26 offset:6240
	ds_write_b32 v70, v27 offset:6244
	ds_write_b32 v70, v28 offset:6248
	ds_write_b32 v70, v29 offset:6252
	s_waitcnt vmcnt(10)
	ds_write_b32 v70, v30 offset:7280
	ds_write_b32 v70, v31 offset:7284
	ds_write_b32 v70, v32 offset:7288
	ds_write_b32 v70, v33 offset:7292
	s_waitcnt vmcnt(9)
	ds_write_b32 v70, v34 offset:8320
	ds_write_b32 v70, v35 offset:8324
	ds_write_b32 v70, v36 offset:8328
	ds_write_b32 v70, v37 offset:8332
	s_waitcnt vmcnt(8)
	ds_write_b32 v70, v38 offset:9360
	ds_write_b32 v70, v39 offset:9364
	ds_write_b32 v70, v40 offset:9368
	ds_write_b32 v70, v41 offset:9372
	s_waitcnt vmcnt(7)
	ds_write_b32 v70, v42 offset:10400
	ds_write_b32 v70, v43 offset:10404
	ds_write_b32 v70, v44 offset:10408
	ds_write_b32 v70, v45 offset:10412
	s_waitcnt vmcnt(6)
	ds_write_b32 v70, v46 offset:11440
	ds_write_b32 v70, v47 offset:11444
	ds_write_b32 v70, v48 offset:11448
	ds_write_b32 v70, v49 offset:11452
	s_waitcnt vmcnt(5)
	ds_write_b32 v70, v50 offset:12480
	ds_write_b32 v70, v51 offset:12484
	ds_write_b32 v70, v52 offset:12488
	ds_write_b32 v70, v53 offset:12492
	s_waitcnt vmcnt(4)
; #define LAS __attribute__((address_space(3)))
; __device__ __forceinline__ unsigned cvtpk(float lo, float hi) { f32x2_t v = {lo, hi}; bf16x2_t b = __builtin_convertvector(v, bf16x2_t); return __builtin_bit_cast(unsigned, b); }
; __device__ __forceinline__ void tr_all(const float* const* in, unsigned char* ws, LAS float* scr, int gw, int ngw, int lane, const TrRanges rg) {
;     ...
;         const LAS float* rp = scr + (8 * (lane & 7)) * 65 + (lane >> 3);
; #pragma unroll
;         for (int j = 0; j < 8; ++j) { const LAS float* s = rp + 8 * j;
;             u32x4 o; o.x = cvtpk(s[0 * 65] * g0[0], s[1 * 65] * g0[1]); o.y = cvtpk(s[2 * 65] * g0[2], s[3 * 65] * g0[3]);
;             o.z = cvtpk(s[4 * 65] * g1[0], s[5 * 65] * g1[1]); o.w = cvtpk(s[6 * 65] * g1[2], s[7 * 65] * g1[3]);
;             if (cur.nts) __builtin_nontemporal_store(o, (u32x4*)(cur.dst + (size_t)(8 * j) * cur.K)); else *(u32x4*)(cur.dst + (size_t)(8 * j) * cur.K) = o; }
;         asm volatile("s_waitcnt lgkmcnt(0)" ::: "memory");
	ds_write_b32 v70, v54 offset:13520
	ds_write_b32 v70, v55 offset:13524
	ds_write_b32 v70, v56 offset:13528
	ds_write_b32 v70, v57 offset:13532
	s_waitcnt vmcnt(3)
	ds_write_b32 v70, v58 offset:14560
	ds_write_b32 v70, v59 offset:14564
	ds_write_b32 v70, v60 offset:14568
	ds_write_b32 v70, v61 offset:14572
	s_waitcnt vmcnt(2)
	ds_write_b32 v70, v62 offset:15600
	ds_write_b32 v70, v63 offset:15604
	ds_write_b32 v70, v64 offset:15608
	ds_write_b32 v70, v65 offset:15612
	s_add_u32 s100, s84, 0x8f00000
	s_addc_u32 s101, s85, 0
	s_waitcnt vmcnt(0) lgkmcnt(0)
	ds_read_b32 v2, v71
	ds_read_b32 v3, v71 offset:260
	ds_read_b32 v4, v71 offset:520
	ds_read_b32 v5, v71 offset:780
	ds_read_b32 v6, v71 offset:1040
	ds_read_b32 v7, v71 offset:1300
	ds_read_b32 v8, v71 offset:1560
	ds_read_b32 v9, v71 offset:1820
	ds_read_b32 v10, v71 offset:32
	ds_read_b32 v11, v71 offset:292
	ds_read_b32 v12, v71 offset:552
	ds_read_b32 v13, v71 offset:812
	ds_read_b32 v14, v71 offset:1072
	ds_read_b32 v15, v71 offset:1332
	ds_read_b32 v16, v71 offset:1592
	ds_read_b32 v17, v71 offset:1852
	ds_read_b32 v18, v71 offset:64
	ds_read_b32 v19, v71 offset:324
	ds_read_b32 v20, v71 offset:584
	ds_read_b32 v21, v71 offset:844
	ds_read_b32 v22, v71 offset:1104
	ds_read_b32 v23, v71 offset:1364
	ds_read_b32 v24, v71 offset:1624
	ds_read_b32 v25, v71 offset:1884
	ds_read_b32 v26, v71 offset:96
	ds_read_b32 v27, v71 offset:356
	ds_read_b32 v28, v71 offset:616
	ds_read_b32 v29, v71 offset:876
	ds_read_b32 v30, v71 offset:1136
	ds_read_b32 v31, v71 offset:1396
	ds_read_b32 v32, v71 offset:1656
	ds_read_b32 v33, v71 offset:1916
	ds_read_b32 v34, v71 offset:128
	ds_read_b32 v35, v71 offset:388
	ds_read_b32 v36, v71 offset:648
	ds_read_b32 v37, v71 offset:908
	ds_read_b32 v38, v71 offset:1168
	ds_read_b32 v39, v71 offset:1428
	ds_read_b32 v40, v71 offset:1688
	ds_read_b32 v41, v71 offset:1948
	ds_read_b32 v42, v71 offset:160
	ds_read_b32 v43, v71 offset:420
	ds_read_b32 v44, v71 offset:680
	ds_read_b32 v45, v71 offset:940
	ds_read_b32 v46, v71 offset:1200
	ds_read_b32 v47, v71 offset:1460
	ds_read_b32 v48, v71 offset:1720
	ds_read_b32 v49, v71 offset:1980
	ds_read_b32 v50, v71 offset:192
	ds_read_b32 v51, v71 offset:452
	ds_read_b32 v52, v71 offset:712
	ds_read_b32 v53, v71 offset:972
	ds_read_b32 v54, v71 offset:1232
	ds_read_b32 v55, v71 offset:1492
	ds_read_b32 v56, v71 offset:1752
	ds_read_b32 v57, v71 offset:2012
	ds_read_b32 v58, v71 offset:224
	ds_read_b32 v59, v71 offset:484
	ds_read_b32 v60, v71 offset:744
	ds_read_b32 v61, v71 offset:1004
	ds_read_b32 v62, v71 offset:1264
	ds_read_b32 v63, v71 offset:1524
	ds_read_b32 v64, v71 offset:1784
	ds_read_b32 v65, v71 offset:2044
	s_waitcnt lgkmcnt(15)
	v_mul_f32_e32 v2, v2, v74
	v_mul_f32_e32 v3, v3, v75
	v_mul_f32_e32 v4, v4, v76
	v_mul_f32_e32 v5, v5, v77
	v_mul_f32_e32 v6, v6, v78
	v_mul_f32_e32 v7, v7, v79
	v_mul_f32_e32 v8, v8, v80
	v_mul_f32_e32 v9, v9, v81
	v_cvt_pk_bf16_f32 v192, v2, v3
	v_cvt_pk_bf16_f32 v193, v4, v5
	v_cvt_pk_bf16_f32 v194, v6, v7
	v_cvt_pk_bf16_f32 v195, v8, v9
	global_store_dwordx4 v72, v[192:195], s[100:101] nt
	s_waitcnt lgkmcnt(15)
	v_mul_f32_e32 v10, v10, v74
	v_mul_f32_e32 v11, v11, v75
	v_mul_f32_e32 v12, v12, v76
	v_mul_f32_e32 v13, v13, v77
	v_mul_f32_e32 v14, v14, v78
	v_mul_f32_e32 v15, v15, v79
	v_mul_f32_e32 v16, v16, v80
	v_mul_f32_e32 v17, v17, v81
	v_cvt_pk_bf16_f32 v196, v10, v11
	v_cvt_pk_bf16_f32 v197, v12, v13
	v_cvt_pk_bf16_f32 v198, v14, v15
	v_cvt_pk_bf16_f32 v199, v16, v17
	v_add_u32_e32 v68, 0x8000, v72
	global_store_dwordx4 v68, v[196:199], s[100:101] nt
	s_waitcnt lgkmcnt(15)
	v_mul_f32_e32 v18, v18, v74
	v_mul_f32_e32 v19, v19, v75
	v_mul_f32_e32 v20, v20, v76
	v_mul_f32_e32 v21, v21, v77
	v_mul_f32_e32 v22, v22, v78
	v_mul_f32_e32 v23, v23, v79
	v_mul_f32_e32 v24, v24, v80
	v_mul_f32_e32 v25, v25, v81
	v_cvt_pk_bf16_f32 v200, v18, v19
	v_cvt_pk_bf16_f32 v201, v20, v21
	v_cvt_pk_bf16_f32 v202, v22, v23
	v_cvt_pk_bf16_f32 v203, v24, v25
	v_add_u32_e32 v67, 0x10000, v72
	global_store_dwordx4 v67, v[200:203], s[100:101] nt
	s_waitcnt lgkmcnt(15)
	v_mul_f32_e32 v26, v26, v74
	v_mul_f32_e32 v27, v27, v75
	v_mul_f32_e32 v28, v28, v76
	v_mul_f32_e32 v29, v29, v77
	v_mul_f32_e32 v30, v30, v78
	v_mul_f32_e32 v31, v31, v79
	v_mul_f32_e32 v32, v32, v80
	v_mul_f32_e32 v33, v33, v81
	v_cvt_pk_bf16_f32 v204, v26, v27
	v_cvt_pk_bf16_f32 v205, v28, v29
	v_cvt_pk_bf16_f32 v206, v30, v31
	v_cvt_pk_bf16_f32 v207, v32, v33
	v_add_u32_e32 v68, 0x18000, v72
	global_store_dwordx4 v68, v[204:207], s[100:101] nt
	s_waitcnt lgkmcnt(15)
	v_mul_f32_e32 v34, v34, v74
	v_mul_f32_e32 v35, v35, v75
	v_mul_f32_e32 v36, v36, v76
	v_mul_f32_e32 v37, v37, v77
	v_mul_f32_e32 v38, v38, v78
	v_mul_f32_e32 v39, v39, v79
	v_mul_f32_e32 v40, v40, v80
	v_mul_f32_e32 v41, v41, v81
	v_cvt_pk_bf16_f32 v208, v34, v35
	v_cvt_pk_bf16_f32 v209, v36, v37
	v_cvt_pk_bf16_f32 v210, v38, v39
	v_cvt_pk_bf16_f32 v211, v40, v41
	v_add_u32_e32 v67, 0x20000, v72
	global_store_dwordx4 v67, v[208:211], s[100:101] nt
	s_waitcnt lgkmcnt(15)
	v_mul_f32_e32 v42, v42, v74
	v_mul_f32_e32 v43, v43, v75
	v_mul_f32_e32 v44, v44, v76
	v_mul_f32_e32 v45, v45, v77
	v_mul_f32_e32 v46, v46, v78
	v_mul_f32_e32 v47, v47, v79
	v_mul_f32_e32 v48, v48, v80
	v_mul_f32_e32 v49, v49, v81
	v_cvt_pk_bf16_f32 v212, v42, v43
	v_cvt_pk_bf16_f32 v213, v44, v45
	v_cvt_pk_bf16_f32 v214, v46, v47
	v_cvt_pk_bf16_f32 v215, v48, v49
	v_add_u32_e32 v68, 0x28000, v72
	global_store_dwordx4 v68, v[212:215], s[100:101] nt
	s_waitcnt lgkmcnt(8)
	v_mul_f32_e32 v50, v50, v74
	v_mul_f32_e32 v51, v51, v75
	v_mul_f32_e32 v52, v52, v76
	v_mul_f32_e32 v53, v53, v77
	v_mul_f32_e32 v54, v54, v78
	v_mul_f32_e32 v55, v55, v79
	v_mul_f32_e32 v56, v56, v80
	v_mul_f32_e32 v57, v57, v81
	v_cvt_pk_bf16_f32 v216, v50, v51
	v_cvt_pk_bf16_f32 v217, v52, v53
	v_cvt_pk_bf16_f32 v218, v54, v55
	v_cvt_pk_bf16_f32 v219, v56, v57
	v_add_u32_e32 v67, 0x30000, v72
	global_store_dwordx4 v67, v[216:219], s[100:101] nt
	s_waitcnt lgkmcnt(0)
	v_mul_f32_e32 v58, v58, v74
	v_mul_f32_e32 v59, v59, v75
	v_mul_f32_e32 v60, v60, v76
	v_mul_f32_e32 v61, v61, v77
	v_mul_f32_e32 v62, v62, v78
	v_mul_f32_e32 v63, v63, v79
	v_mul_f32_e32 v64, v64, v80
	v_mul_f32_e32 v65, v65, v81
	v_cvt_pk_bf16_f32 v220, v58, v59
	v_cvt_pk_bf16_f32 v221, v60, v61
	v_cvt_pk_bf16_f32 v222, v62, v63
	v_cvt_pk_bf16_f32 v223, v64, v65
	v_add_u32_e32 v68, 0x38000, v72
	global_store_dwordx4 v68, v[220:223], s[100:101] nt
	s_branch .LBB0_339

; #define LAS __attribute__((address_space(3)))
; #define TR_LOAD(p) __builtin_nontemporal_load(p)
; __device__ __forceinline__ TrItem tr_decode(int it, const float* const* in, unsigned char* ws, int lane) {
;     ...
;     const int rh = r >> 3, rl = r & 7, nq = ndb >> DL, kbh = rh / nq, dbh = rh - kbh * nq;
;     const int kb = (kbh << KL) + (rl >> DL), db = (dbh << DL) + (rl & ((1 << DL) - 1)), d0 = db * 64, k0 = kb * 64;
;     ...
;     const int kb = r / ndb, db = r - kb * ndb, d0 = db * 64, k0 = kb * 64;
;     ...
;     const int blk = d0 + 32 * ((lane & 15) >> 3);
;     const float* src = W; int s0 = blk;
;     if (kind == 1) { const int pn = blk >> 8, bj = (blk >> 7) & 1, o = blk & 127; src = bj ? W2 : W; s0 = pn * 128 + o; }
;     else if (kind == 2) s0 = win_src(blk);
;     TrItem t; t.src = src + (size_t)(k0 + (lane >> 4)) * N + s0 + 4 * (lane & 7); t.gain = gain ? gain + k0 + 8 * (lane & 7) : nullptr;
;     t.dst = WT + (size_t)(d0 + (lane >> 3)) * K + k0 + 8 * (lane & 7); t.N = N; t.K = K; t.nts = nts && TR_NTS;
; __device__ __forceinline__ void tr_all(const float* const* in, unsigned char* ws, LAS float* scr, int gw, int ngw, int lane, const TrRanges rg) {
;     ...
;     for (int i = 0; i < 16; ++i) v[i] = TR_LOAD((const f32x4*)(cur.src + (size_t)(4 * i) * cur.N));
;     for (int it = gw; it < TR_CNT; it += ngw) {
;         const int nit = it + ngw; const bool hn = nit < TR_CNT;
;         TrItem nx = cur; f32x4 w[16];
;         if (hn) { nx = tr_decode(rg.item(nit), in, ws, lane);
; #pragma unroll
;             for (int i = 0; i < 16; ++i) w[i] = TR_LOAD((const f32x4*)(nx.src + (size_t)(4 * i) * nx.N)); }
;         LAS float* wp = scr + (lane >> 4) * 65 + 4 * (lane & 15);
; #pragma unroll
;         for (int i = 0; i < 16; ++i) { wp[(4 * i) * 65 + 0] = v[i][0]; wp[(4 * i) * 65 + 1] = v[i][1]; wp[(4 * i) * 65 + 2] = v[i][2]; wp[(4 * i) * 65 + 3] = v[i][3]; }
.Lseam_cv_1:
	s_cmp_lt_u32 s98, 2
	s_cbranch_scc1 .LBB0_570
	s_cmp_gt_u32 s98, 5
	s_cbranch_scc1 .Lseam_cv_1_1
	s_mov_b64 exec, -1
	s_lshl_b32 s99, s87, 2
	s_add_i32 s99, s99, s98
	s_add_i32 s99, s99, 0xdfe
	s_lshr_b32 s100, s99, 3
	s_mul_i32 s101, s100, 0x5d2
	s_lshr_b32 s101, s101, 16
	s_mul_i32 vcc_lo, s101, 44
	s_sub_i32 s100, s100, vcc_lo
	s_and_b32 vcc_lo, s99, 7
	s_lshr_b32 vcc_hi, vcc_lo, 2
	s_lshl_b32 s101, s101, 1
	s_add_i32 s101, s101, vcc_hi
	s_and_b32 vcc_lo, vcc_lo, 3
	s_lshl_b32 s100, s100, 2
	s_add_i32 s100, s100, vcc_lo
	s_lshl_b32 s101, s101, 6
	s_lshl_b32 s100, s100, 6
	v_and_b32_e32 v66, 63, v1
	v_lshrrev_b32_e32 v67, 4, v66
	v_and_b32_e32 v68, 15, v66
	v_and_b32_e32 v73, 7, v66
	v_lshrrev_b32_e32 v72, 3, v66
	s_mul_i32 s99, s98, 0x4100
	v_mul_u32_u24_e32 v70, 0x104, v67
	v_lshl_add_u32 v70, v68, 4, v70
	v_add_u32_e32 v70, s99, v70
	v_mul_u32_u24_e32 v71, 0x820, v73
	v_lshl_add_u32 v71, v72, 2, v71
	v_add_u32_e32 v71, s99, v71
	s_mul_i32 s99, s101, 0x1600
	s_lshr_b32 vcc_lo, s100, 8
	s_lshl_b32 vcc_lo, vcc_lo, 7
	s_add_i32 s99, s99, vcc_lo
	s_and_b32 vcc_lo, s100, 0x7f
	s_add_i32 s99, s99, vcc_lo
	s_lshl_b32 s99, s99, 2
	v_mul_u32_u24_e32 v69, 0x5800, v67
	v_lshl_add_u32 v69, v68, 4, v69
	v_add_u32_e32 v69, s99, v69
	s_lshl_b32 s99, s100, 12
	s_lshl_b32 vcc_lo, s101, 1
	s_add_i32 s99, s99, vcc_lo
	v_lshlrev_b32_e32 v72, 12, v72
	v_lshl_add_u32 v72, v73, 4, v72
	v_add_u32_e32 v72, s99, v72
	s_lshl_b32 s99, s101, 2
	v_lshlrev_b32_e32 v73, 5, v73
	v_add_u32_e32 v73, s99, v73
	s_nop 0
	s_bitcmp1_b32 s100, 7
	v_readlane_b32 s100, v254, 6
	v_readlane_b32 s101, v254, 7
	v_readlane_b32 s98, v254, 8
	v_readlane_b32 s99, v254, 9
	s_nop 3
	s_cselect_b32 s100, s98, s100
	s_cselect_b32 s101, s99, s101
	v_readlane_b32 s98, v254, 4
	v_readlane_b32 s99, v254, 5
	global_load_dwordx4 v[2:5], v69, s[100:101] nt
	v_add_u32_e32 v68, 0x16000, v69
	global_load_dwordx4 v[6:9], v68, s[100:101] nt
	v_add_u32_e32 v67, 0x2c000, v69
	global_load_dwordx4 v[10:13], v67, s[100:101] nt
	v_add_u32_e32 v68, 0x42000, v69
	global_load_dwordx4 v[14:17], v68, s[100:101] nt
	v_add_u32_e32 v67, 0x58000, v69
	global_load_dwordx4 v[18:21], v67, s[100:101] nt
	v_add_u32_e32 v68, 0x6e000, v69
	global_load_dwordx4 v[22:25], v68, s[100:101] nt
	v_add_u32_e32 v67, 0x84000, v69
	global_load_dwordx4 v[26:29], v67, s[100:101] nt
	v_add_u32_e32 v68, 0x9a000, v69
	global_load_dwordx4 v[30:33], v68, s[100:101] nt
	v_add_u32_e32 v67, 0xb0000, v69
	global_load_dwordx4 v[34:37], v67, s[100:101] nt
	v_add_u32_e32 v68, 0xc6000, v69
	global_load_dwordx4 v[38:41], v68, s[100:101] nt
	v_add_u32_e32 v67, 0xdc000, v69
	global_load_dwordx4 v[42:45], v67, s[100:101] nt
	v_add_u32_e32 v68, 0xf2000, v69
	global_load_dwordx4 v[46:49], v68, s[100:101] nt
	v_add_u32_e32 v67, 0x108000, v69
	global_load_dwordx4 v[50:53], v67, s[100:101] nt
	v_add_u32_e32 v68, 0x11e000, v69
	global_load_dwordx4 v[54:57], v68, s[100:101] nt
	v_add_u32_e32 v67, 0x134000, v69
	global_load_dwordx4 v[58:61], v67, s[100:101] nt
	v_add_u32_e32 v68, 0x14a000, v69
	global_load_dwordx4 v[62:65], v68, s[100:101] nt
	global_load_dwordx4 v[74:77], v73, s[98:99]
	global_load_dwordx4 v[78:81], v73, s[98:99] offset:16
	s_waitcnt vmcnt(17)
	ds_write_b32 v70, v2
	ds_write_b32 v70, v3 offset:4
	ds_write_b32 v70, v4 offset:8
	ds_write_b32 v70, v5 offset:12
	s_waitcnt vmcnt(16)
	ds_write_b32 v70, v6 offset:1040
	ds_write_b32 v70, v7 offset:1044
	ds_write_b32 v70, v8 offset:1048
	ds_write_b32 v70, v9 offset:1052
	s_waitcnt vmcnt(15)
	ds_write_b32 v70, v10 offset:2080
	ds_write_b32 v70, v11 offset:2084
	ds_write_b32 v70, v12 offset:2088
	ds_write_b32 v70, v13 offset:2092
	s_waitcnt vmcnt(14)
	ds_write_b32 v70, v14 offset:3120
	ds_write_b32 v70, v15 offset:3124
	ds_write_b32 v70, v16 offset:3128
	ds_write_b32 v70, v17 offset:3132
	s_waitcnt vmcnt(13)
	ds_write_b32 v70, v18 offset:4160
	ds_write_b32 v70, v19 offset:4164
	ds_write_b32 v70, v20 offset:4168
	ds_write_b32 v70, v21 offset:4172
	s_waitcnt vmcnt(12)
	ds_write_b32 v70, v22 offset:5200
	ds_write_b32 v70, v23 offset:5204
	ds_write_b32 v70, v24 offset:5208
	ds_write_b32 v70, v25 offset:5212
	s_waitcnt vmcnt(11)
	ds_write_b32 v70, v26 offset:6240
	ds_write_b32 v70, v27 offset:6244
	ds_write_b32 v70, v28 offset:6248
	ds_write_b32 v70, v29 offset:6252
	s_waitcnt vmcnt(10)
	ds_write_b32 v70, v30 offset:7280
	ds_write_b32 v70, v31 offset:7284
	ds_write_b32 v70, v32 offset:7288
	ds_write_b32 v70, v33 offset:7292
	s_waitcnt vmcnt(9)
	ds_write_b32 v70, v34 offset:8320
	ds_write_b32 v70, v35 offset:8324
	ds_write_b32 v70, v36 offset:8328
	ds_write_b32 v70, v37 offset:8332
	s_waitcnt vmcnt(8)
	ds_write_b32 v70, v38 offset:9360
	ds_write_b32 v70, v39 offset:9364
	ds_write_b32 v70, v40 offset:9368
	ds_write_b32 v70, v41 offset:9372
	s_waitcnt vmcnt(7)
	ds_write_b32 v70, v42 offset:10400
	ds_write_b32 v70, v43 offset:10404
	ds_write_b32 v70, v44 offset:10408
	ds_write_b32 v70, v45 offset:10412
	s_waitcnt vmcnt(6)
	ds_write_b32 v70, v46 offset:11440
	ds_write_b32 v70, v47 offset:11444
	ds_write_b32 v70, v48 offset:11448
	ds_write_b32 v70, v49 offset:11452
	s_waitcnt vmcnt(5)
	ds_write_b32 v70, v50 offset:12480
	ds_write_b32 v70, v51 offset:12484
	ds_write_b32 v70, v52 offset:12488
	ds_write_b32 v70, v53 offset:12492
	s_waitcnt vmcnt(4)
	ds_write_b32 v70, v54 offset:13520
	ds_write_b32 v70, v55 offset:13524
	ds_write_b32 v70, v56 offset:13528
	ds_write_b32 v70, v57 offset:13532
	s_waitcnt vmcnt(3)
	ds_write_b32 v70, v58 offset:14560
	ds_write_b32 v70, v59 offset:14564
	ds_write_b32 v70, v60 offset:14568
	ds_write_b32 v70, v61 offset:14572
	s_waitcnt vmcnt(2)
; #define LAS __attribute__((address_space(3)))
; __device__ __forceinline__ unsigned cvtpk(float lo, float hi) { f32x2_t v = {lo, hi}; bf16x2_t b = __builtin_convertvector(v, bf16x2_t); return __builtin_bit_cast(unsigned, b); }
; __device__ __forceinline__ void tr_all(const float* const* in, unsigned char* ws, LAS float* scr, int gw, int ngw, int lane, const TrRanges rg) {
;     ...
;         const LAS float* rp = scr + (8 * (lane & 7)) * 65 + (lane >> 3);
; #pragma unroll
;         for (int j = 0; j < 8; ++j) { const LAS float* s = rp + 8 * j;
;             u32x4 o; o.x = cvtpk(s[0 * 65] * g0[0], s[1 * 65] * g0[1]); o.y = cvtpk(s[2 * 65] * g0[2], s[3 * 65] * g0[3]);
;             o.z = cvtpk(s[4 * 65] * g1[0], s[5 * 65] * g1[1]); o.w = cvtpk(s[6 * 65] * g1[2], s[7 * 65] * g1[3]);
;             if (cur.nts) __builtin_nontemporal_store(o, (u32x4*)(cur.dst + (size_t)(8 * j) * cur.K)); else *(u32x4*)(cur.dst + (size_t)(8 * j) * cur.K) = o; }
;         asm volatile("s_waitcnt lgkmcnt(0)" ::: "memory");
	ds_write_b32 v70, v62 offset:15600
	ds_write_b32 v70, v63 offset:15604
	ds_write_b32 v70, v64 offset:15608
	ds_write_b32 v70, v65 offset:15612
	s_add_u32 s100, s84, 0x8f00000
	s_addc_u32 s101, s85, 0
	s_waitcnt vmcnt(0) lgkmcnt(0)
	ds_read_b32 v2, v71
	ds_read_b32 v3, v71 offset:260
	ds_read_b32 v4, v71 offset:520
	ds_read_b32 v5, v71 offset:780
	ds_read_b32 v6, v71 offset:1040
	ds_read_b32 v7, v71 offset:1300
	ds_read_b32 v8, v71 offset:1560
	ds_read_b32 v9, v71 offset:1820
	ds_read_b32 v10, v71 offset:32
	ds_read_b32 v11, v71 offset:292
	ds_read_b32 v12, v71 offset:552
	ds_read_b32 v13, v71 offset:812
	ds_read_b32 v14, v71 offset:1072
	ds_read_b32 v15, v71 offset:1332
	ds_read_b32 v16, v71 offset:1592
	ds_read_b32 v17, v71 offset:1852
	ds_read_b32 v18, v71 offset:64
	ds_read_b32 v19, v71 offset:324
	ds_read_b32 v20, v71 offset:584
	ds_read_b32 v21, v71 offset:844
	ds_read_b32 v22, v71 offset:1104
	ds_read_b32 v23, v71 offset:1364
	ds_read_b32 v24, v71 offset:1624
	ds_read_b32 v25, v71 offset:1884
	ds_read_b32 v26, v71 offset:96
	ds_read_b32 v27, v71 offset:356
	ds_read_b32 v28, v71 offset:616
	ds_read_b32 v29, v71 offset:876
	ds_read_b32 v30, v71 offset:1136
	ds_read_b32 v31, v71 offset:1396
	ds_read_b32 v32, v71 offset:1656
	ds_read_b32 v33, v71 offset:1916
	ds_read_b32 v34, v71 offset:128
	ds_read_b32 v35, v71 offset:388
	ds_read_b32 v36, v71 offset:648
	ds_read_b32 v37, v71 offset:908
	ds_read_b32 v38, v71 offset:1168
	ds_read_b32 v39, v71 offset:1428
	ds_read_b32 v40, v71 offset:1688
	ds_read_b32 v41, v71 offset:1948
	ds_read_b32 v42, v71 offset:160
	ds_read_b32 v43, v71 offset:420
	ds_read_b32 v44, v71 offset:680
	ds_read_b32 v45, v71 offset:940
	ds_read_b32 v46, v71 offset:1200
	ds_read_b32 v47, v71 offset:1460
	ds_read_b32 v48, v71 offset:1720
	ds_read_b32 v49, v71 offset:1980
	ds_read_b32 v50, v71 offset:192
	ds_read_b32 v51, v71 offset:452
	ds_read_b32 v52, v71 offset:712
	ds_read_b32 v53, v71 offset:972
	ds_read_b32 v54, v71 offset:1232
	ds_read_b32 v55, v71 offset:1492
	ds_read_b32 v56, v71 offset:1752
	ds_read_b32 v57, v71 offset:2012
	ds_read_b32 v58, v71 offset:224
	ds_read_b32 v59, v71 offset:484
	ds_read_b32 v60, v71 offset:744
	ds_read_b32 v61, v71 offset:1004
	ds_read_b32 v62, v71 offset:1264
	ds_read_b32 v63, v71 offset:1524
	ds_read_b32 v64, v71 offset:1784
	ds_read_b32 v65, v71 offset:2044
	s_waitcnt lgkmcnt(15)
	v_mul_f32_e32 v2, v2, v74
	v_mul_f32_e32 v3, v3, v75
	v_mul_f32_e32 v4, v4, v76
	v_mul_f32_e32 v5, v5, v77
	v_mul_f32_e32 v6, v6, v78
	v_mul_f32_e32 v7, v7, v79
	v_mul_f32_e32 v8, v8, v80
	v_mul_f32_e32 v9, v9, v81
	v_cvt_pk_bf16_f32 v192, v2, v3
	v_cvt_pk_bf16_f32 v193, v4, v5
	v_cvt_pk_bf16_f32 v194, v6, v7
	v_cvt_pk_bf16_f32 v195, v8, v9
	global_store_dwordx4 v72, v[192:195], s[100:101] nt
	s_waitcnt lgkmcnt(15)
	v_mul_f32_e32 v10, v10, v74
	v_mul_f32_e32 v11, v11, v75
	v_mul_f32_e32 v12, v12, v76
	v_mul_f32_e32 v13, v13, v77
	v_mul_f32_e32 v14, v14, v78
	v_mul_f32_e32 v15, v15, v79
	v_mul_f32_e32 v16, v16, v80
	v_mul_f32_e32 v17, v17, v81
	v_cvt_pk_bf16_f32 v196, v10, v11
	v_cvt_pk_bf16_f32 v197, v12, v13
	v_cvt_pk_bf16_f32 v198, v14, v15
	v_cvt_pk_bf16_f32 v199, v16, v17
	v_add_u32_e32 v68, 0x8000, v72
	global_store_dwordx4 v68, v[196:199], s[100:101] nt
	s_waitcnt lgkmcnt(15)
	v_mul_f32_e32 v18, v18, v74
	v_mul_f32_e32 v19, v19, v75
	v_mul_f32_e32 v20, v20, v76
	v_mul_f32_e32 v21, v21, v77
	v_mul_f32_e32 v22, v22, v78
	v_mul_f32_e32 v23, v23, v79
	v_mul_f32_e32 v24, v24, v80
	v_mul_f32_e32 v25, v25, v81
	v_cvt_pk_bf16_f32 v200, v18, v19
	v_cvt_pk_bf16_f32 v201, v20, v21
	v_cvt_pk_bf16_f32 v202, v22, v23
	v_cvt_pk_bf16_f32 v203, v24, v25
	v_add_u32_e32 v67, 0x10000, v72
	global_store_dwordx4 v67, v[200:203], s[100:101] nt
	s_waitcnt lgkmcnt(15)
	v_mul_f32_e32 v26, v26, v74
	v_mul_f32_e32 v27, v27, v75
	v_mul_f32_e32 v28, v28, v76
	v_mul_f32_e32 v29, v29, v77
	v_mul_f32_e32 v30, v30, v78
	v_mul_f32_e32 v31, v31, v79
	v_mul_f32_e32 v32, v32, v80
	v_mul_f32_e32 v33, v33, v81
	v_cvt_pk_bf16_f32 v204, v26, v27
	v_cvt_pk_bf16_f32 v205, v28, v29
	v_cvt_pk_bf16_f32 v206, v30, v31
	v_cvt_pk_bf16_f32 v207, v32, v33
	v_add_u32_e32 v68, 0x18000, v72
	global_store_dwordx4 v68, v[204:207], s[100:101] nt
	s_waitcnt lgkmcnt(15)
	v_mul_f32_e32 v34, v34, v74
	v_mul_f32_e32 v35, v35, v75
	v_mul_f32_e32 v36, v36, v76
	v_mul_f32_e32 v37, v37, v77
	v_mul_f32_e32 v38, v38, v78
	v_mul_f32_e32 v39, v39, v79
	v_mul_f32_e32 v40, v40, v80
	v_mul_f32_e32 v41, v41, v81
	v_cvt_pk_bf16_f32 v208, v34, v35
	v_cvt_pk_bf16_f32 v209, v36, v37
	v_cvt_pk_bf16_f32 v210, v38, v39
	v_cvt_pk_bf16_f32 v211, v40, v41
	v_add_u32_e32 v67, 0x20000, v72
	global_store_dwordx4 v67, v[208:211], s[100:101] nt
	s_waitcnt lgkmcnt(15)
	v_mul_f32_e32 v42, v42, v74
	v_mul_f32_e32 v43, v43, v75
	v_mul_f32_e32 v44, v44, v76
	v_mul_f32_e32 v45, v45, v77
	v_mul_f32_e32 v46, v46, v78
	v_mul_f32_e32 v47, v47, v79
	v_mul_f32_e32 v48, v48, v80
	v_mul_f32_e32 v49, v49, v81
	v_cvt_pk_bf16_f32 v212, v42, v43
	v_cvt_pk_bf16_f32 v213, v44, v45
	v_cvt_pk_bf16_f32 v214, v46, v47
	v_cvt_pk_bf16_f32 v215, v48, v49
	v_add_u32_e32 v68, 0x28000, v72
	global_store_dwordx4 v68, v[212:215], s[100:101] nt
	s_waitcnt lgkmcnt(8)
	v_mul_f32_e32 v50, v50, v74
	v_mul_f32_e32 v51, v51, v75
	v_mul_f32_e32 v52, v52, v76
	v_mul_f32_e32 v53, v53, v77
	v_mul_f32_e32 v54, v54, v78
	v_mul_f32_e32 v55, v55, v79
	v_mul_f32_e32 v56, v56, v80
	v_mul_f32_e32 v57, v57, v81
	v_cvt_pk_bf16_f32 v216, v50, v51
	v_cvt_pk_bf16_f32 v217, v52, v53
	v_cvt_pk_bf16_f32 v218, v54, v55
	v_cvt_pk_bf16_f32 v219, v56, v57
	v_add_u32_e32 v67, 0x30000, v72
	global_store_dwordx4 v67, v[216:219], s[100:101] nt
	s_waitcnt lgkmcnt(0)
; #define LAS __attribute__((address_space(3)))
; #define TR_LOAD(p) __builtin_nontemporal_load(p)
; __device__ __forceinline__ TrItem tr_decode(int it, const float* const* in, unsigned char* ws, int lane) {
;     ...
;     const int rh = r >> 3, rl = r & 7, nq = ndb >> DL, kbh = rh / nq, dbh = rh - kbh * nq;
;     const int kb = (kbh << KL) + (rl >> DL), db = (dbh << DL) + (rl & ((1 << DL) - 1)), d0 = db * 64, k0 = kb * 64;
;     ...
;     const int kb = r / ndb, db = r - kb * ndb, d0 = db * 64, k0 = kb * 64;
;     ...
;     const int blk = d0 + 32 * ((lane & 15) >> 3);
;     const float* src = W; int s0 = blk;
;     if (kind == 1) { const int pn = blk >> 8, bj = (blk >> 7) & 1, o = blk & 127; src = bj ? W2 : W; s0 = pn * 128 + o; }
;     else if (kind == 2) s0 = win_src(blk);
;     TrItem t; t.src = src + (size_t)(k0 + (lane >> 4)) * N + s0 + 4 * (lane & 7); t.gain = gain ? gain + k0 + 8 * (lane & 7) : nullptr;
;     t.dst = WT + (size_t)(d0 + (lane >> 3)) * K + k0 + 8 * (lane & 7); t.N = N; t.K = K; t.nts = nts && TR_NTS;
; __device__ __forceinline__ void tr_all(const float* const* in, unsigned char* ws, LAS float* scr, int gw, int ngw, int lane, const TrRanges rg) {
;     ...
;     for (int i = 0; i < 16; ++i) v[i] = TR_LOAD((const f32x4*)(cur.src + (size_t)(4 * i) * cur.N));
;     for (int it = gw; it < TR_CNT; it += ngw) {
;         const int nit = it + ngw; const bool hn = nit < TR_CNT;
;         TrItem nx = cur; f32x4 w[16];
;         if (hn) { nx = tr_decode(rg.item(nit), in, ws, lane);
; #pragma unroll
;             for (int i = 0; i < 16; ++i) w[i] = TR_LOAD((const f32x4*)(nx.src + (size_t)(4 * i) * nx.N)); }
;         LAS float* wp = scr + (lane >> 4) * 65 + 4 * (lane & 15);
; #pragma unroll
;         for (int i = 0; i < 16; ++i) { wp[(4 * i) * 65 + 0] = v[i][0]; wp[(4 * i) * 65 + 1] = v[i][1]; wp[(4 * i) * 65 + 2] = v[i][2]; wp[(4 * i) * 65 + 3] = v[i][3]; }
	v_mul_f32_e32 v58, v58, v74
	v_mul_f32_e32 v59, v59, v75
	v_mul_f32_e32 v60, v60, v76
	v_mul_f32_e32 v61, v61, v77
	v_mul_f32_e32 v62, v62, v78
	v_mul_f32_e32 v63, v63, v79
	v_mul_f32_e32 v64, v64, v80
	v_mul_f32_e32 v65, v65, v81
	v_cvt_pk_bf16_f32 v220, v58, v59
	v_cvt_pk_bf16_f32 v221, v60, v61
	v_cvt_pk_bf16_f32 v222, v62, v63
	v_cvt_pk_bf16_f32 v223, v64, v65
	v_add_u32_e32 v68, 0x38000, v72
	global_store_dwordx4 v68, v[220:223], s[100:101] nt
	v_readfirstlane_b32 s98, v1
	s_nop 3
	s_lshr_b32 s98, s98, 6
	s_lshl_b32 s99, s87, 2
	s_add_i32 s99, s99, s98
	s_add_i32 s99, s99, 0x11fe
	s_lshr_b32 s100, s99, 3
	s_mul_i32 s101, s100, 0x5d2
	s_lshr_b32 s101, s101, 16
	s_mul_i32 vcc_lo, s101, 44
	s_sub_i32 s100, s100, vcc_lo
	s_and_b32 vcc_lo, s99, 7
	s_lshr_b32 vcc_hi, vcc_lo, 2
	s_lshl_b32 s101, s101, 1
	s_add_i32 s101, s101, vcc_hi
	s_and_b32 vcc_lo, vcc_lo, 3
	s_lshl_b32 s100, s100, 2
	s_add_i32 s100, s100, vcc_lo
	s_lshl_b32 s101, s101, 6
	s_lshl_b32 s100, s100, 6
	v_and_b32_e32 v66, 63, v1
	v_lshrrev_b32_e32 v67, 4, v66
	v_and_b32_e32 v68, 15, v66
	v_and_b32_e32 v73, 7, v66
	v_lshrrev_b32_e32 v72, 3, v66
	s_mul_i32 s99, s98, 0x4100
	v_mul_u32_u24_e32 v70, 0x104, v67
	v_lshl_add_u32 v70, v68, 4, v70
	v_add_u32_e32 v70, s99, v70
	v_mul_u32_u24_e32 v71, 0x820, v73
	v_lshl_add_u32 v71, v72, 2, v71
	v_add_u32_e32 v71, s99, v71
	s_mul_i32 s99, s101, 0x1600
	s_lshr_b32 vcc_lo, s100, 8
	s_lshl_b32 vcc_lo, vcc_lo, 7
	s_add_i32 s99, s99, vcc_lo
	s_and_b32 vcc_lo, s100, 0x7f
	s_add_i32 s99, s99, vcc_lo
	s_lshl_b32 s99, s99, 2
	v_mul_u32_u24_e32 v69, 0x5800, v67
	v_lshl_add_u32 v69, v68, 4, v69
	v_add_u32_e32 v69, s99, v69
	s_lshl_b32 s99, s100, 12
	s_lshl_b32 vcc_lo, s101, 1
	s_add_i32 s99, s99, vcc_lo
	v_lshlrev_b32_e32 v72, 12, v72
	v_lshl_add_u32 v72, v73, 4, v72
	v_add_u32_e32 v72, s99, v72
	s_lshl_b32 s99, s101, 2
	v_lshlrev_b32_e32 v73, 5, v73
	v_add_u32_e32 v73, s99, v73
	s_nop 0
	s_bitcmp1_b32 s100, 7
	v_readlane_b32 s100, v254, 6
	v_readlane_b32 s101, v254, 7
	v_readlane_b32 s98, v254, 8
	v_readlane_b32 s99, v254, 9
	s_nop 3
	s_cselect_b32 s100, s98, s100
	s_cselect_b32 s101, s99, s101
	v_readlane_b32 s98, v254, 4
	v_readlane_b32 s99, v254, 5
	global_load_dwordx4 v[2:5], v69, s[100:101] nt
	v_add_u32_e32 v68, 0x16000, v69
	global_load_dwordx4 v[6:9], v68, s[100:101] nt
	v_add_u32_e32 v67, 0x2c000, v69
	global_load_dwordx4 v[10:13], v67, s[100:101] nt
	v_add_u32_e32 v68, 0x42000, v69
	global_load_dwordx4 v[14:17], v68, s[100:101] nt
	v_add_u32_e32 v67, 0x58000, v69
	global_load_dwordx4 v[18:21], v67, s[100:101] nt
	v_add_u32_e32 v68, 0x6e000, v69
	global_load_dwordx4 v[22:25], v68, s[100:101] nt
	v_add_u32_e32 v67, 0x84000, v69
	global_load_dwordx4 v[26:29], v67, s[100:101] nt
	v_add_u32_e32 v68, 0x9a000, v69
	global_load_dwordx4 v[30:33], v68, s[100:101] nt
	v_add_u32_e32 v67, 0xb0000, v69
	global_load_dwordx4 v[34:37], v67, s[100:101] nt
	v_add_u32_e32 v68, 0xc6000, v69
	global_load_dwordx4 v[38:41], v68, s[100:101] nt
	v_add_u32_e32 v67, 0xdc000, v69
	global_load_dwordx4 v[42:45], v67, s[100:101] nt
	v_add_u32_e32 v68, 0xf2000, v69
	global_load_dwordx4 v[46:49], v68, s[100:101] nt
	v_add_u32_e32 v67, 0x108000, v69
	global_load_dwordx4 v[50:53], v67, s[100:101] nt
	v_add_u32_e32 v68, 0x11e000, v69
	global_load_dwordx4 v[54:57], v68, s[100:101] nt
	v_add_u32_e32 v67, 0x134000, v69
	global_load_dwordx4 v[58:61], v67, s[100:101] nt
	v_add_u32_e32 v68, 0x14a000, v69
	global_load_dwordx4 v[62:65], v68, s[100:101] nt
	global_load_dwordx4 v[74:77], v73, s[98:99]
	global_load_dwordx4 v[78:81], v73, s[98:99] offset:16
	s_waitcnt vmcnt(17)
	ds_write_b32 v70, v2
	ds_write_b32 v70, v3 offset:4
	ds_write_b32 v70, v4 offset:8
	ds_write_b32 v70, v5 offset:12
	s_waitcnt vmcnt(16)
	ds_write_b32 v70, v6 offset:1040
	ds_write_b32 v70, v7 offset:1044
	ds_write_b32 v70, v8 offset:1048
	ds_write_b32 v70, v9 offset:1052
	s_waitcnt vmcnt(15)
	ds_write_b32 v70, v10 offset:2080
	ds_write_b32 v70, v11 offset:2084
	ds_write_b32 v70, v12 offset:2088
	ds_write_b32 v70, v13 offset:2092
	s_waitcnt vmcnt(14)
	ds_write_b32 v70, v14 offset:3120
	ds_write_b32 v70, v15 offset:3124
	ds_write_b32 v70, v16 offset:3128
	ds_write_b32 v70, v17 offset:3132
	s_waitcnt vmcnt(13)
	ds_write_b32 v70, v18 offset:4160
	ds_write_b32 v70, v19 offset:4164
	ds_write_b32 v70, v20 offset:4168
	ds_write_b32 v70, v21 offset:4172
	s_waitcnt vmcnt(12)
	ds_write_b32 v70, v22 offset:5200
	ds_write_b32 v70, v23 offset:5204
	ds_write_b32 v70, v24 offset:5208
	ds_write_b32 v70, v25 offset:5212
	s_waitcnt vmcnt(11)
	ds_write_b32 v70, v26 offset:6240
	ds_write_b32 v70, v27 offset:6244
	ds_write_b32 v70, v28 offset:6248
	ds_write_b32 v70, v29 offset:6252
	s_waitcnt vmcnt(10)
	ds_write_b32 v70, v30 offset:7280
	ds_write_b32 v70, v31 offset:7284
	ds_write_b32 v70, v32 offset:7288
	ds_write_b32 v70, v33 offset:7292
	s_waitcnt vmcnt(9)
	ds_write_b32 v70, v34 offset:8320
	ds_write_b32 v70, v35 offset:8324
	ds_write_b32 v70, v36 offset:8328
	ds_write_b32 v70, v37 offset:8332
	s_waitcnt vmcnt(8)
	ds_write_b32 v70, v38 offset:9360
	ds_write_b32 v70, v39 offset:9364
	ds_write_b32 v70, v40 offset:9368
	ds_write_b32 v70, v41 offset:9372
	s_waitcnt vmcnt(7)
	ds_write_b32 v70, v42 offset:10400
	ds_write_b32 v70, v43 offset:10404
	ds_write_b32 v70, v44 offset:10408
	ds_write_b32 v70, v45 offset:10412
	s_waitcnt vmcnt(6)
	ds_write_b32 v70, v46 offset:11440
	ds_write_b32 v70, v47 offset:11444
	ds_write_b32 v70, v48 offset:11448
	ds_write_b32 v70, v49 offset:11452
	s_waitcnt vmcnt(5)
	ds_write_b32 v70, v50 offset:12480
	ds_write_b32 v70, v51 offset:12484
	ds_write_b32 v70, v52 offset:12488
	ds_write_b32 v70, v53 offset:12492
	s_waitcnt vmcnt(4)
; #define LAS __attribute__((address_space(3)))
; __device__ __forceinline__ unsigned cvtpk(float lo, float hi) { f32x2_t v = {lo, hi}; bf16x2_t b = __builtin_convertvector(v, bf16x2_t); return __builtin_bit_cast(unsigned, b); }
; __device__ __forceinline__ void tr_all(const float* const* in, unsigned char* ws, LAS float* scr, int gw, int ngw, int lane, const TrRanges rg) {
;     ...
;         const LAS float* rp = scr + (8 * (lane & 7)) * 65 + (lane >> 3);
; #pragma unroll
;         for (int j = 0; j < 8; ++j) { const LAS float* s = rp + 8 * j;
;             u32x4 o; o.x = cvtpk(s[0 * 65] * g0[0], s[1 * 65] * g0[1]); o.y = cvtpk(s[2 * 65] * g0[2], s[3 * 65] * g0[3]);
;             o.z = cvtpk(s[4 * 65] * g1[0], s[5 * 65] * g1[1]); o.w = cvtpk(s[6 * 65] * g1[2], s[7 * 65] * g1[3]);
;             if (cur.nts) __builtin_nontemporal_store(o, (u32x4*)(cur.dst + (size_t)(8 * j) * cur.K)); else *(u32x4*)(cur.dst + (size_t)(8 * j) * cur.K) = o; }
;         asm volatile("s_waitcnt lgkmcnt(0)" ::: "memory");
	ds_write_b32 v70, v54 offset:13520
	ds_write_b32 v70, v55 offset:13524
	ds_write_b32 v70, v56 offset:13528
	ds_write_b32 v70, v57 offset:13532
	s_waitcnt vmcnt(3)
	ds_write_b32 v70, v58 offset:14560
	ds_write_b32 v70, v59 offset:14564
	ds_write_b32 v70, v60 offset:14568
	ds_write_b32 v70, v61 offset:14572
	s_waitcnt vmcnt(2)
	ds_write_b32 v70, v62 offset:15600
	ds_write_b32 v70, v63 offset:15604
	ds_write_b32 v70, v64 offset:15608
	ds_write_b32 v70, v65 offset:15612
	s_add_u32 s100, s84, 0x8f00000
	s_addc_u32 s101, s85, 0
	s_waitcnt vmcnt(0) lgkmcnt(0)
	ds_read_b32 v2, v71
	ds_read_b32 v3, v71 offset:260
	ds_read_b32 v4, v71 offset:520
	ds_read_b32 v5, v71 offset:780
	ds_read_b32 v6, v71 offset:1040
	ds_read_b32 v7, v71 offset:1300
	ds_read_b32 v8, v71 offset:1560
	ds_read_b32 v9, v71 offset:1820
	ds_read_b32 v10, v71 offset:32
	ds_read_b32 v11, v71 offset:292
	ds_read_b32 v12, v71 offset:552
	ds_read_b32 v13, v71 offset:812
	ds_read_b32 v14, v71 offset:1072
	ds_read_b32 v15, v71 offset:1332
	ds_read_b32 v16, v71 offset:1592
	ds_read_b32 v17, v71 offset:1852
	ds_read_b32 v18, v71 offset:64
	ds_read_b32 v19, v71 offset:324
	ds_read_b32 v20, v71 offset:584
	ds_read_b32 v21, v71 offset:844
	ds_read_b32 v22, v71 offset:1104
	ds_read_b32 v23, v71 offset:1364
	ds_read_b32 v24, v71 offset:1624
	ds_read_b32 v25, v71 offset:1884
	ds_read_b32 v26, v71 offset:96
	ds_read_b32 v27, v71 offset:356
	ds_read_b32 v28, v71 offset:616
	ds_read_b32 v29, v71 offset:876
	ds_read_b32 v30, v71 offset:1136
	ds_read_b32 v31, v71 offset:1396
	ds_read_b32 v32, v71 offset:1656
	ds_read_b32 v33, v71 offset:1916
	ds_read_b32 v34, v71 offset:128
	ds_read_b32 v35, v71 offset:388
	ds_read_b32 v36, v71 offset:648
	ds_read_b32 v37, v71 offset:908
	ds_read_b32 v38, v71 offset:1168
	ds_read_b32 v39, v71 offset:1428
	ds_read_b32 v40, v71 offset:1688
	ds_read_b32 v41, v71 offset:1948
	ds_read_b32 v42, v71 offset:160
	ds_read_b32 v43, v71 offset:420
	ds_read_b32 v44, v71 offset:680
	ds_read_b32 v45, v71 offset:940
	ds_read_b32 v46, v71 offset:1200
	ds_read_b32 v47, v71 offset:1460
	ds_read_b32 v48, v71 offset:1720
	ds_read_b32 v49, v71 offset:1980
	ds_read_b32 v50, v71 offset:192
	ds_read_b32 v51, v71 offset:452
	ds_read_b32 v52, v71 offset:712
	ds_read_b32 v53, v71 offset:972
	ds_read_b32 v54, v71 offset:1232
	ds_read_b32 v55, v71 offset:1492
	ds_read_b32 v56, v71 offset:1752
	ds_read_b32 v57, v71 offset:2012
	ds_read_b32 v58, v71 offset:224
	ds_read_b32 v59, v71 offset:484
	ds_read_b32 v60, v71 offset:744
	ds_read_b32 v61, v71 offset:1004
	ds_read_b32 v62, v71 offset:1264
	ds_read_b32 v63, v71 offset:1524
	ds_read_b32 v64, v71 offset:1784
	ds_read_b32 v65, v71 offset:2044
	s_waitcnt lgkmcnt(15)
	v_mul_f32_e32 v2, v2, v74
	v_mul_f32_e32 v3, v3, v75
	v_mul_f32_e32 v4, v4, v76
	v_mul_f32_e32 v5, v5, v77
	v_mul_f32_e32 v6, v6, v78
	v_mul_f32_e32 v7, v7, v79
	v_mul_f32_e32 v8, v8, v80
	v_mul_f32_e32 v9, v9, v81
	v_cvt_pk_bf16_f32 v192, v2, v3
	v_cvt_pk_bf16_f32 v193, v4, v5
	v_cvt_pk_bf16_f32 v194, v6, v7
	v_cvt_pk_bf16_f32 v195, v8, v9
	global_store_dwordx4 v72, v[192:195], s[100:101] nt
	s_waitcnt lgkmcnt(15)
	v_mul_f32_e32 v10, v10, v74
	v_mul_f32_e32 v11, v11, v75
	v_mul_f32_e32 v12, v12, v76
	v_mul_f32_e32 v13, v13, v77
	v_mul_f32_e32 v14, v14, v78
	v_mul_f32_e32 v15, v15, v79
	v_mul_f32_e32 v16, v16, v80
	v_mul_f32_e32 v17, v17, v81
	v_cvt_pk_bf16_f32 v196, v10, v11
	v_cvt_pk_bf16_f32 v197, v12, v13
	v_cvt_pk_bf16_f32 v198, v14, v15
	v_cvt_pk_bf16_f32 v199, v16, v17
	v_add_u32_e32 v68, 0x8000, v72
	global_store_dwordx4 v68, v[196:199], s[100:101] nt
	s_waitcnt lgkmcnt(15)
	v_mul_f32_e32 v18, v18, v74
	v_mul_f32_e32 v19, v19, v75
	v_mul_f32_e32 v20, v20, v76
	v_mul_f32_e32 v21, v21, v77
	v_mul_f32_e32 v22, v22, v78
	v_mul_f32_e32 v23, v23, v79
	v_mul_f32_e32 v24, v24, v80
	v_mul_f32_e32 v25, v25, v81
	v_cvt_pk_bf16_f32 v200, v18, v19
	v_cvt_pk_bf16_f32 v201, v20, v21
	v_cvt_pk_bf16_f32 v202, v22, v23
	v_cvt_pk_bf16_f32 v203, v24, v25
	v_add_u32_e32 v67, 0x10000, v72
	global_store_dwordx4 v67, v[200:203], s[100:101] nt
	s_waitcnt lgkmcnt(15)
	v_mul_f32_e32 v26, v26, v74
	v_mul_f32_e32 v27, v27, v75
	v_mul_f32_e32 v28, v28, v76
	v_mul_f32_e32 v29, v29, v77
	v_mul_f32_e32 v30, v30, v78
	v_mul_f32_e32 v31, v31, v79
	v_mul_f32_e32 v32, v32, v80
	v_mul_f32_e32 v33, v33, v81
	v_cvt_pk_bf16_f32 v204, v26, v27
	v_cvt_pk_bf16_f32 v205, v28, v29
	v_cvt_pk_bf16_f32 v206, v30, v31
	v_cvt_pk_bf16_f32 v207, v32, v33
	v_add_u32_e32 v68, 0x18000, v72
	global_store_dwordx4 v68, v[204:207], s[100:101] nt
	s_waitcnt lgkmcnt(15)
	v_mul_f32_e32 v34, v34, v74
	v_mul_f32_e32 v35, v35, v75
	v_mul_f32_e32 v36, v36, v76
	v_mul_f32_e32 v37, v37, v77
	v_mul_f32_e32 v38, v38, v78
	v_mul_f32_e32 v39, v39, v79
	v_mul_f32_e32 v40, v40, v80
	v_mul_f32_e32 v41, v41, v81
	v_cvt_pk_bf16_f32 v208, v34, v35
	v_cvt_pk_bf16_f32 v209, v36, v37
	v_cvt_pk_bf16_f32 v210, v38, v39
	v_cvt_pk_bf16_f32 v211, v40, v41
	v_add_u32_e32 v67, 0x20000, v72
	global_store_dwordx4 v67, v[208:211], s[100:101] nt
	s_waitcnt lgkmcnt(15)
	v_mul_f32_e32 v42, v42, v74
	v_mul_f32_e32 v43, v43, v75
	v_mul_f32_e32 v44, v44, v76
	v_mul_f32_e32 v45, v45, v77
	v_mul_f32_e32 v46, v46, v78
	v_mul_f32_e32 v47, v47, v79
	v_mul_f32_e32 v48, v48, v80
	v_mul_f32_e32 v49, v49, v81
	v_cvt_pk_bf16_f32 v212, v42, v43
	v_cvt_pk_bf16_f32 v213, v44, v45
	v_cvt_pk_bf16_f32 v214, v46, v47
	v_cvt_pk_bf16_f32 v215, v48, v49
	v_add_u32_e32 v68, 0x28000, v72
	global_store_dwordx4 v68, v[212:215], s[100:101] nt
	s_waitcnt lgkmcnt(8)
	v_mul_f32_e32 v50, v50, v74
	v_mul_f32_e32 v51, v51, v75
	v_mul_f32_e32 v52, v52, v76
	v_mul_f32_e32 v53, v53, v77
	v_mul_f32_e32 v54, v54, v78
	v_mul_f32_e32 v55, v55, v79
	v_mul_f32_e32 v56, v56, v80
	v_mul_f32_e32 v57, v57, v81
	v_cvt_pk_bf16_f32 v216, v50, v51
	v_cvt_pk_bf16_f32 v217, v52, v53
	v_cvt_pk_bf16_f32 v218, v54, v55
	v_cvt_pk_bf16_f32 v219, v56, v57
	v_add_u32_e32 v67, 0x30000, v72
	global_store_dwordx4 v67, v[216:219], s[100:101] nt
	s_waitcnt lgkmcnt(0)
	v_mul_f32_e32 v58, v58, v74
	v_mul_f32_e32 v59, v59, v75
	v_mul_f32_e32 v60, v60, v76
	v_mul_f32_e32 v61, v61, v77
	v_mul_f32_e32 v62, v62, v78
	v_mul_f32_e32 v63, v63, v79
	v_mul_f32_e32 v64, v64, v80
	v_mul_f32_e32 v65, v65, v81
	v_cvt_pk_bf16_f32 v220, v58, v59
	v_cvt_pk_bf16_f32 v221, v60, v61
	v_cvt_pk_bf16_f32 v222, v62, v63
	v_cvt_pk_bf16_f32 v223, v64, v65
	v_add_u32_e32 v68, 0x38000, v72
	global_store_dwordx4 v68, v[220:223], s[100:101] nt
	s_branch .LBB0_570

;     __device__ __forceinline__ void fused(f32x4 (&acc)[2][2][4][2], const Unit& u, int wr, int wc, int fr, int fq, PG8_LAS unsigned char* lds, int wid, int lane) const {
;     ...
;             __hip_atomic_store(xbuf + (size_t)(u.pm * 256 + row) * 8 + u.pn, t, __ATOMIC_RELAXED, __HIP_MEMORY_SCOPE_AGENT);
;         }
;         asm volatile("s_waitcnt vmcnt(0)" ::: "memory");
;         unsigned* c = cnt + 64 * u.pm;
;         if (lane == 0) __hip_atomic_fetch_add(c, 1u, __ATOMIC_RELAXED, __HIP_MEMORY_SCOPE_AGENT);
;         if (wid == 0) {
;             unsigned sp = 0;
;             while ((unsigned)__builtin_amdgcn_readfirstlane(__hip_atomic_load(c, __ATOMIC_RELAXED, __HIP_MEMORY_SCOPE_AGENT)) < 64u) { __builtin_amdgcn_s_sleep(2); if (++sp > (1u << 22)) break; }
;             __builtin_amdgcn_fence(__ATOMIC_ACQUIRE, "agent");
;         }
;         asm volatile("s_waitcnt vmcnt(0) lgkmcnt(0)" ::: "memory"); __builtin_amdgcn_s_barrier(); asm volatile("" ::: "memory");
;         if (lane < 32) {
;             const float* slot = xbuf + (size_t)(u.pm * 256 + row) * 8; float t = 0.f;
; #pragma unroll
;             for (int k = 0; k < 8; ++k) t += __hip_atomic_load(slot + k, __ATOMIC_RELAXED, __HIP_MEMORY_SCOPE_AGENT);
.Lseam_cv_2:
	s_cmp_lt_u32 s98, 2
	s_cbranch_scc1 .LBB0_681
	s_cmp_gt_u32 s98, 2
	s_cbranch_scc1 .LBB0_681
	s_mov_b64 exec, -1
	v_and_b32_e32 v66, 63, v1
	s_lshl_b32 s99, s87, 10
	v_lshlrev_b32_e32 v66, 4, v66
	v_add_u32_e32 v66, s99, v66
	s_add_u32 s100, s84, 0x80000
	s_addc_u32 s101, s85, 0
	v_mov_b32_e32 v2, 0xbf800000
	v_mov_b32_e32 v3, 0xbf800000
	v_mov_b32_e32 v4, 0xbf800000
	v_mov_b32_e32 v5, 0xbf800000
	global_store_dwordx4 v66, v[2:5], s[100:101] sc1
